# batched serialized loads in nsa_posbias and nsa_posbias_reduce + attn_sw epilogue batching/hoist/permlane
# speedup vs baseline: 1.0035x; 1.0035x over previous
; __device__ __forceinline__ void nsa_posbias(const Ctx& c, const float* pos, const float* w1, float* PBP) {
;     for (int o = ((c.gw & 3) == 3) ? (c.gw >> 2) : 512; o < 512; o += (c.NGW >> 2)) { const int ten = o >> 8, nb = (o >> 6) & 3, ks = o & 63, n = nb * 64 + c.lane; float a = 0.f;
; #pragma unroll 16
;         for (int k = 0; k < 64; ++k) a += pos[ten * 4096 + ks * 64 + k] * w1[((size_t)ten * 4096 + ks * 64 + k) * 256 + n];
;         PBP[(ten * 64 + ks) * 256 + n] = a; }
.LBB0_1480:
	s_add_u32 s16, s7, s8
	s_addc_u32 s17, s15, s9
	global_load_dwordx4 v[4:7], v9, s[16:17] offset:48
	global_load_dwordx4 v[12:15], v9, s[16:17] offset:32
	global_load_dwordx4 v[16:19], v9, s[16:17] offset:16
	global_load_dwordx4 v[20:23], v9, s[16:17]
	s_movk_i32 s16, 0xd000
	v_add_co_u32_e32 v24, vcc, s16, v10
	s_nop 1
	v_addc_co_u32_e32 v25, vcc, -1, v11, vcc
	s_movk_i32 s16, 0xe000
	v_add_co_u32_e32 v26, vcc, s16, v10
	s_nop 1
	v_addc_co_u32_e32 v27, vcc, -1, v11, vcc
	s_movk_i32 s16, 0xf000
	v_add_co_u32_e32 v28, vcc, s16, v10
	s_nop 1
	v_addc_co_u32_e32 v29, vcc, -1, v11, vcc
	global_load_dword v32, v[24:25], off offset:-3072
	global_load_dword v33, v[24:25], off offset:-2048
	global_load_dword v34, v[24:25], off offset:-1024
	global_load_dword v35, v[26:27], off offset:-4096
	global_load_dword v36, v[26:27], off offset:-3072
	global_load_dword v37, v[26:27], off offset:-2048
	global_load_dword v38, v[26:27], off offset:-1024
	global_load_dword v39, v[26:27], off
	global_load_dword v40, v[28:29], off offset:-3072
	global_load_dword v41, v[28:29], off offset:-2048
	global_load_dword v42, v[28:29], off offset:-1024
	global_load_dword v43, v[10:11], off offset:-4096
	global_load_dword v44, v[10:11], off offset:-3072
	global_load_dword v45, v[10:11], off offset:-2048
	global_load_dword v46, v[10:11], off offset:-1024
	global_load_dword v47, v[10:11], off
	s_add_u32 s8, s8, 64
	s_addc_u32 s9, s9, 0
	s_mov_b64 s[16:17], 0x4000
	v_lshl_add_u64 v[10:11], v[10:11], 0, s[16:17]
	s_waitcnt vmcnt(15)
	v_fmac_f32_e32 v3, v20, v32
	s_waitcnt vmcnt(14)
	v_fmac_f32_e32 v3, v21, v33
	s_waitcnt vmcnt(13)
	v_fmac_f32_e32 v3, v22, v34
	s_waitcnt vmcnt(12)
	v_fmac_f32_e32 v3, v23, v35
	s_waitcnt vmcnt(11)
	v_fmac_f32_e32 v3, v16, v36
	s_waitcnt vmcnt(10)
	v_fmac_f32_e32 v3, v17, v37
	s_waitcnt vmcnt(9)
	v_fmac_f32_e32 v3, v18, v38
	s_waitcnt vmcnt(8)
	v_fmac_f32_e32 v3, v19, v39
	s_waitcnt vmcnt(7)
	v_fmac_f32_e32 v3, v12, v40
	s_waitcnt vmcnt(6)
	v_fmac_f32_e32 v3, v13, v41
	s_waitcnt vmcnt(5)
	v_fmac_f32_e32 v3, v14, v42
	s_waitcnt vmcnt(4)
	v_fmac_f32_e32 v3, v15, v43
	s_waitcnt vmcnt(3)
	v_fmac_f32_e32 v3, v4, v44
	s_waitcnt vmcnt(2)
	v_fmac_f32_e32 v3, v5, v45
	s_waitcnt vmcnt(1)
	v_fmac_f32_e32 v3, v6, v46
	s_waitcnt vmcnt(0)
	v_fmac_f32_e32 v3, v7, v47
	s_cmpk_eq_i32 s8, 0x100
	s_cbranch_scc0 .LBB0_1480
	s_and_b32 s7, s10, 0xc0
	s_and_b32 s8, s10, 63
	v_or_b32_e32 v4, s7, v164
	s_lshl_b32 s6, s6, 14
	s_lshl_b32 s7, s8, 8
	s_or_b32 s6, s6, s7
	v_or_b32_e32 v4, s6, v4
	v_ashrrev_i32_e32 v5, 31, v4
	s_add_i32 s10, s10, s12
	s_add_i32 s11, s11, s12
	v_lshl_add_u64 v[4:5], v[4:5], 2, s[2:3]
	s_cmpk_gt_i32 s10, 0x1ff
	global_store_dword v[4:5], v3, off
	s_cbranch_scc0 .LBB0_1479

; __device__ __forceinline__ void nsa_posbias_reduce(const Ctx& c, const float* PBP, float* PB) {
;     if (c.vcu == 0) { const int ten = c.tid >> 8, n = c.tid & 255; float a = 0.f;
; #pragma unroll 16
;         for (int ks = 0; ks < 64; ++ks) a += PBP[(ten * 64 + ks) * 256 + n];
;         PB[c.tid] = a; }
; }
.LBB0_1722:
	v_lshl_add_u64 v[38:39], v[34:35], 0, s[2:3]
	global_load_dword v40, v[38:39], off
	v_lshl_add_u64 v[38:39], v[32:33], 0, s[2:3]
	global_load_dword v41, v[38:39], off
	v_lshl_add_u64 v[38:39], v[30:31], 0, s[2:3]
	global_load_dword v42, v[38:39], off
	v_lshl_add_u64 v[38:39], v[28:29], 0, s[2:3]
	global_load_dword v43, v[38:39], off
	v_lshl_add_u64 v[38:39], v[26:27], 0, s[2:3]
	global_load_dword v44, v[38:39], off
	v_lshl_add_u64 v[38:39], v[24:25], 0, s[2:3]
	global_load_dword v45, v[38:39], off
	v_lshl_add_u64 v[38:39], v[22:23], 0, s[2:3]
	global_load_dword v46, v[38:39], off
	v_lshl_add_u64 v[38:39], v[20:21], 0, s[2:3]
	global_load_dword v47, v[38:39], off
	v_lshl_add_u64 v[38:39], v[18:19], 0, s[2:3]
	global_load_dword v48, v[38:39], off
	v_lshl_add_u64 v[38:39], v[16:17], 0, s[2:3]
	global_load_dword v49, v[38:39], off
	v_lshl_add_u64 v[38:39], v[14:15], 0, s[2:3]
	global_load_dword v50, v[38:39], off
	v_lshl_add_u64 v[38:39], v[12:13], 0, s[2:3]
	global_load_dword v51, v[38:39], off
	v_lshl_add_u64 v[38:39], v[10:11], 0, s[2:3]
	global_load_dword v52, v[38:39], off
	v_lshl_add_u64 v[38:39], v[8:9], 0, s[2:3]
	global_load_dword v53, v[38:39], off
	v_lshl_add_u64 v[38:39], v[6:7], 0, s[2:3]
	global_load_dword v54, v[38:39], off
	v_lshl_add_u64 v[38:39], v[4:5], 0, s[2:3]
	global_load_dword v55, v[38:39], off
	s_add_u32 s2, s2, 0x4000
	s_addc_u32 s3, s3, 0
	s_waitcnt vmcnt(15)
	v_add_f32_e32 v37, v37, v40
	s_waitcnt vmcnt(14)
	v_add_f32_e32 v37, v37, v41
	s_waitcnt vmcnt(13)
	v_add_f32_e32 v37, v37, v42
	s_waitcnt vmcnt(12)
	v_add_f32_e32 v37, v37, v43
	s_waitcnt vmcnt(11)
	v_add_f32_e32 v37, v37, v44
	s_waitcnt vmcnt(10)
	v_add_f32_e32 v37, v37, v45
	s_waitcnt vmcnt(9)
	v_add_f32_e32 v37, v37, v46
	s_waitcnt vmcnt(8)
	v_add_f32_e32 v37, v37, v47
	s_waitcnt vmcnt(7)
	v_add_f32_e32 v37, v37, v48
	s_waitcnt vmcnt(6)
	v_add_f32_e32 v37, v37, v49
	s_waitcnt vmcnt(5)
	v_add_f32_e32 v37, v37, v50
	s_waitcnt vmcnt(4)
	v_add_f32_e32 v37, v37, v51
	s_waitcnt vmcnt(3)
	v_add_f32_e32 v37, v37, v52
	s_waitcnt vmcnt(2)
	v_add_f32_e32 v37, v37, v53
	s_waitcnt vmcnt(1)
	v_add_f32_e32 v37, v37, v54
	s_waitcnt vmcnt(0)
	v_add_f32_e32 v37, v37, v55
	s_cmp_eq_u32 s2, 0x10000
	s_cbranch_scc0 .LBB0_1722
	v_lshlrev_b32_e32 v4, 2, v0
	global_store_dword v4, v37, s[8:9]
	v_mov_b32_e32 v4, v3
